# phase rebalancing: all 512 sample-state GLA items streamed in P2b (beside the scan) instead of 256 in P2a + 256 in P2b
# speedup vs baseline: 1.0063x; 1.0063x over previous
.LBB0_493:
	v_writelane_b32 v254, s83, 28
	s_or_b64 exec, exec, s[4:5]
	v_mov_b32_e32 v66, v234
	s_waitcnt lgkmcnt(0)
	s_barrier
	v_writelane_b32 v254, s81, 29
	s_load_dwordx2 s[4:5], s[0:1], 64
	s_waitcnt lgkmcnt(0)
	s_cmpk_lg_i32 s92, 0x100
	v_writelane_b32 v254, s4, 30
	s_cselect_b64 s[8:9], -1, 0
	s_cmpk_eq_i32 s92, 0x100
	v_writelane_b32 v254, s5, 31
	s_load_dwordx2 s[4:5], s[0:1], 0x48
	s_waitcnt lgkmcnt(0)
	s_cselect_b32 s33, 0, 0
	v_writelane_b32 v254, s4, 32
	v_add_u32_e32 v144, s81, v66
	s_movk_i32 s3, 0x100
	v_writelane_b32 v254, s5, 33
	s_load_dwordx2 s[4:5], s[0:1], 24
	s_waitcnt lgkmcnt(0)
	v_ashrrev_i32_e32 v145, 31, v144
	v_writelane_b32 v254, s4, 34
	v_lshl_add_u32 v208, v144, 2, 0
	v_ashrrev_i32_e32 v209, 7, v144
	v_writelane_b32 v254, s5, 35
	s_load_dwordx2 s[4:5], s[0:1], 0x58
	s_waitcnt lgkmcnt(0)
	s_nop 0
	v_writelane_b32 v254, s4, 36
	s_nop 1
	v_writelane_b32 v254, s5, 37
	s_load_dwordx2 s[4:5], s[0:1], 16
	s_waitcnt lgkmcnt(0)
	s_nop 0
	v_writelane_b32 v254, s4, 38
	s_nop 1
	v_writelane_b32 v254, s5, 39
	s_load_dwordx2 s[4:5], s[0:1], 0xa0
	s_waitcnt lgkmcnt(0)
	s_nop 0
	v_writelane_b32 v254, s4, 40
	s_nop 1
	v_writelane_b32 v254, s5, 41
	s_and_b32 s4, s2, 1
	s_cmp_eq_u32 s4, 0
	s_cselect_b64 s[6:7], -1, 0
	s_cmp_eq_u32 s4, 1
	s_cselect_b64 s[4:5], -1, 0
	v_writelane_b32 v254, s4, 42
	s_cmp_ge_i32 s2, s33
	s_nop 0
	v_writelane_b32 v254, s5, 43
	s_cselect_b64 s[4:5], -1, 0
	v_writelane_b32 v254, s6, 44
	s_or_b64 s[4:5], s[6:7], s[4:5]
	s_and_b64 vcc, exec, s[4:5]
	v_writelane_b32 v254, s7, 45
	s_cbranch_vccnz .LBB0_500
	v_and_b32_e32 v1, 0x7f, v144
	v_lshlrev_b32_e32 v2, 6, v209
	v_lshlrev_b32_e32 v3, 11, v209
	v_lshlrev_b32_e32 v32, 4, v1
	s_add_u32 s20, s96, 0x2d400000
	v_cmp_gt_i32_e64 s[4:5], s3, v144
	v_add3_u32 v50, 0, v3, v32
	s_addc_u32 s21, s97, 0
	s_ashr_i32 s3, s2, 31
	v_ashrrev_i32_e32 v3, 31, v2
	s_lshl_b64 s[6:7], s[2:3], 19
	v_lshlrev_b64 v[2:3], 11, v[2:3]
	v_lshl_add_u64 v[2:3], s[6:7], 0, v[2:3]
	v_readlane_b32 s6, v254, 38
	v_readlane_b32 s7, v254, 39
	v_lshlrev_b32_e32 v0, 2, v1
	s_ashr_i32 s93, s92, 31
	v_lshl_add_u64 v[34:35], s[6:7], 0, v[2:3]
	v_readlane_b32 s6, v254, 40
	v_readlane_b32 s7, v254, 41
	v_mov_b32_e32 v33, 0
	v_lshl_add_u32 v51, v209, 8, 0
	s_lshl_b64 s[10:11], s[92:93], 19
	v_lshl_add_u64 v[36:37], s[6:7], 0, v[2:3]
	s_movk_i32 s3, 0x2000
	v_mov_b32_e32 v52, 0x3000
	s_movk_i32 s22, 0x4000
	s_movk_i32 s23, 0x6000
	s_mov_b32 s24, 0x8000
	s_mov_b32 s25, 0xa000
	s_mov_b32 s26, 0xc000
	s_mov_b32 s27, 0xe000
	s_mov_b32 s28, 0xf000
	s_mov_b32 s29, 0xbfb8aa3b
	s_mov_b32 s30, 0x800000
	s_mov_b32 s31, 0x3f317217
	s_mov_b32 s34, 0x7f800000
	v_lshlrev_b32_e32 v53, 1, v0
	s_mov_b32 s35, 0x8a10000
	s_mov_b32 s36, 0x8a11000
	s_mov_b32 s37, 0x8a12000
	s_mov_b32 s38, 0x8a13000
	s_mov_b32 s39, 0x8a14000
	s_mov_b32 s40, 0x8a15000
	s_mov_b32 s41, 0x8a16000
	s_mov_b32 s42, 0x8a17000
	s_mov_b64 s[12:13], 0x8000
	s_movk_i32 s43, 0x7fff
	v_mov_b32_e32 v54, 0x41b17218
	s_mov_b32 s44, s2

.LBB0_690:
	s_or_b64 exec, exec, s[4:5]
	v_mov_b32_e32 v50, v234
	s_waitcnt lgkmcnt(0)
	s_barrier
	s_load_dwordx2 s[14:15], s[0:1], 64
	s_waitcnt lgkmcnt(0)
	s_cmpk_eq_i32 s92, 0x100
	s_load_dwordx2 s[16:17], s[0:1], 0x48
	s_waitcnt lgkmcnt(0)
	s_cselect_b64 s[26:27], -1, 0
	s_load_dwordx2 s[22:23], s[0:1], 16
	s_waitcnt lgkmcnt(0)
	s_and_b64 s[4:5], s[26:27], exec
	v_readlane_b32 s4, v254, 44
	s_load_dwordx2 s[24:25], s[0:1], 0xa0
	s_waitcnt lgkmcnt(0)
	v_readlane_b32 s5, v254, 45
	v_add_u32_e32 v136, s93, v50
	s_cselect_b32 s3, 0, 0
	s_andn2_b64 vcc, exec, s[4:5]
	s_cbranch_vccnz .LBB0_699
	s_add_i32 s8, s3, s2
	s_cmpk_gt_i32 s8, 0x1ff
	s_cbranch_scc1 .LBB0_699
	v_ashrrev_i32_e32 v3, 7, v136
	v_lshlrev_b32_e32 v2, 6, v3
	s_add_u32 s33, s96, 0x2d400000
	v_lshlrev_b32_e32 v4, 11, v3
	s_addc_u32 s34, s97, 0
	v_lshl_add_u32 v53, v3, 8, 0
	s_ashr_i32 s9, s8, 31
	v_ashrrev_i32_e32 v3, 31, v2
	v_and_b32_e32 v1, 0x7f, v136
	s_lshl_b64 s[6:7], s[8:9], 19
	v_lshlrev_b64 v[2:3], 11, v[2:3]
	s_movk_i32 s4, 0x100
	v_lshlrev_b32_e32 v0, 2, v1
	v_lshlrev_b32_e32 v32, 4, v1
	v_lshl_add_u64 v[2:3], s[6:7], 0, v[2:3]
	s_ashr_i32 s93, s92, 31
	v_cmp_gt_i32_e64 s[4:5], s4, v136
	v_lshl_add_u32 v51, v136, 2, 0
	v_mov_b32_e32 v33, 0
	v_add3_u32 v52, 0, v4, v32
	v_ashrrev_i32_e32 v137, 31, v136
	v_lshl_add_u64 v[34:35], s[22:23], 0, v[2:3]
	s_lshl_b64 s[10:11], s[92:93], 19
	v_lshl_add_u64 v[36:37], s[24:25], 0, v[2:3]
	s_movk_i32 s9, 0x2000
	v_mov_b32_e32 v54, 0x3000
	s_movk_i32 s35, 0x4000
	s_movk_i32 s36, 0x6000
	s_mov_b32 s37, 0x8000
	s_mov_b32 s38, 0xa000
	s_mov_b32 s39, 0xc000
	s_mov_b32 s40, 0xe000
	s_mov_b32 s41, 0xf000
	s_mov_b32 s42, 0xbfb8aa3b
	s_mov_b32 s43, 0x800000
	s_mov_b32 s44, 0x3f317217
	s_mov_b32 s45, 0x7f800000
	v_lshlrev_b32_e32 v55, 1, v0
	s_mov_b32 s46, 0x8a10000
	s_mov_b32 s47, 0x8a11000
	s_mov_b32 s48, 0x8a12000
	s_mov_b32 s49, 0x8a13000
	s_mov_b32 s50, 0x8a14000
	s_mov_b32 s51, 0x8a15000
	s_mov_b32 s52, 0x8a16000
	s_mov_b32 s53, 0x8a17000
	s_mov_b64 s[12:13], 0x8000
	s_movk_i32 s54, 0x7fff
	v_mov_b32_e32 v56, 0x41b17218
